# mLSTM output items: chunk-state prefix with three rotating half-step landing buffers (two half-steps always in flight)
# baseline (speedup 1.0000x reference)
; template <bool OUT>
; __device__ __forceinline__ void mlstm_item(const bf16* u, bf16* y, float* scratch, const float* convw, const float* ib, const float* fbias, const float* normw, LAS unsigned char* wl, int bh, int c, int lane) {
;     ...
;             const float* s0 = scratch + (size_t)(bh * 16 + cp) * ML_ITEM_F;
;             f32x16 v0[4];
; #pragma unroll
;             for (int blk = 0; blk < 4; ++blk) v0[blk] = *(const f32x16*)(s0 + blk * 1024 + lane * 16);
;             const float n0 = s0[4096 + lane], g0 = s0[4160];
; #pragma unroll
;             for (int blk = 0; blk < 4; ++blk) X[blk >> 1][blk & 1] += v0[blk] * dec;
;             nk += dec * n0;
;             dec *= __expf(g0);
;         }
.LBB0_784:
	v_lshlrev_b32_e32 v172, 6, v214
	v_add_u32_e32 v173, 0x1000, v172
	v_add_u32_e32 v174, 0x2000, v172
	v_add_u32_e32 v175, 0x3000, v172
	v_lshlrev_b32_e32 v176, 2, v214
	v_add_u32_e32 v176, 0x4000, v176
	v_mov_b32_e32 v177, 0x4100
	s_add_i32 s54, s53, -2
	s_add_i32 s0, s3, s54
	s_mul_hi_u32 s1, s0, 0x4200
	s_mulk_i32 s0, 0x4200
	s_add_u32 s0, s60, s0
	s_addc_u32 s1, s61, s1
	global_load_dword v134, v176, s[0:1]
	global_load_dword v135, v177, s[0:1]
	global_load_dwordx4 v[68:71], v172, s[0:1]
	global_load_dwordx4 v[72:75], v172, s[0:1] offset:16
	global_load_dwordx4 v[76:79], v172, s[0:1] offset:32
	global_load_dwordx4 v[80:83], v172, s[0:1] offset:48
	global_load_dwordx4 v[84:87], v173, s[0:1]
	global_load_dwordx4 v[88:91], v173, s[0:1] offset:16
	global_load_dwordx4 v[92:95], v173, s[0:1] offset:32
	global_load_dwordx4 v[96:99], v173, s[0:1] offset:48
	global_load_dwordx4 v[100:103], v174, s[0:1]
	global_load_dwordx4 v[104:107], v174, s[0:1] offset:16
	global_load_dwordx4 v[108:111], v174, s[0:1] offset:32
	global_load_dwordx4 v[112:115], v174, s[0:1] offset:48
	global_load_dwordx4 v[116:119], v175, s[0:1]
	global_load_dwordx4 v[120:123], v175, s[0:1] offset:16
	global_load_dwordx4 v[124:127], v175, s[0:1] offset:32
	global_load_dwordx4 v[128:131], v175, s[0:1] offset:48
	s_add_i32 s55, s54, -1
	s_max_i32 s55, s55, 0
	s_add_i32 s0, s3, s55
	s_mul_hi_u32 s1, s0, 0x4200
	s_mulk_i32 s0, 0x4200
	s_add_u32 s0, s60, s0
	s_addc_u32 s1, s61, s1
	global_load_dword v136, v176, s[0:1]
	global_load_dword v137, v177, s[0:1]
	global_load_dwordx4 v[228:231], v172, s[0:1]
	global_load_dwordx4 v[232:235], v172, s[0:1] offset:16
	global_load_dwordx4 v[236:239], v172, s[0:1] offset:32
	global_load_dwordx4 v[240:243], v172, s[0:1] offset:48
	global_load_dwordx4 v[244:247], v173, s[0:1]
	global_load_dwordx4 v[248:251], v173, s[0:1] offset:16
	global_load_dwordx4 v[164:167], v173, s[0:1] offset:32
	global_load_dwordx4 v[168:171], v173, s[0:1] offset:48
.Lpf_s0:
	s_waitcnt vmcnt(25)
	v_pk_fma_f32 v[4:5], v[68:69], v[2:3], v[4:5] op_sel_hi:[1,0,1]
	v_pk_fma_f32 v[6:7], v[70:71], v[2:3], v[6:7] op_sel_hi:[1,0,1]
	s_waitcnt vmcnt(24)
	v_pk_fma_f32 v[8:9], v[72:73], v[2:3], v[8:9] op_sel_hi:[1,0,1]
	v_pk_fma_f32 v[10:11], v[74:75], v[2:3], v[10:11] op_sel_hi:[1,0,1]
	s_waitcnt vmcnt(23)
	v_pk_fma_f32 v[12:13], v[76:77], v[2:3], v[12:13] op_sel_hi:[1,0,1]
	v_pk_fma_f32 v[14:15], v[78:79], v[2:3], v[14:15] op_sel_hi:[1,0,1]
	s_waitcnt vmcnt(22)
	v_pk_fma_f32 v[16:17], v[80:81], v[2:3], v[16:17] op_sel_hi:[1,0,1]
	v_pk_fma_f32 v[18:19], v[82:83], v[2:3], v[18:19] op_sel_hi:[1,0,1]
	s_waitcnt vmcnt(21)
	v_pk_fma_f32 v[20:21], v[84:85], v[2:3], v[20:21] op_sel_hi:[1,0,1]
	v_pk_fma_f32 v[22:23], v[86:87], v[2:3], v[22:23] op_sel_hi:[1,0,1]
	s_waitcnt vmcnt(20)
	v_pk_fma_f32 v[24:25], v[88:89], v[2:3], v[24:25] op_sel_hi:[1,0,1]
	v_pk_fma_f32 v[26:27], v[90:91], v[2:3], v[26:27] op_sel_hi:[1,0,1]
	s_waitcnt vmcnt(19)
	v_pk_fma_f32 v[28:29], v[92:93], v[2:3], v[28:29] op_sel_hi:[1,0,1]
	v_pk_fma_f32 v[30:31], v[94:95], v[2:3], v[30:31] op_sel_hi:[1,0,1]
	s_waitcnt vmcnt(18)
	v_pk_fma_f32 v[32:33], v[96:97], v[2:3], v[32:33] op_sel_hi:[1,0,1]
	v_pk_fma_f32 v[34:35], v[98:99], v[2:3], v[34:35] op_sel_hi:[1,0,1]
	s_add_i32 s55, s54, -1
	s_max_i32 s55, s55, 0
	s_add_i32 s0, s3, s55
	s_mul_hi_u32 s1, s0, 0x4200
	s_mulk_i32 s0, 0x4200
	s_add_u32 s0, s60, s0
	s_addc_u32 s1, s61, s1
	global_load_dwordx4 v[68:71], v174, s[0:1]
	global_load_dwordx4 v[72:75], v174, s[0:1] offset:16
	global_load_dwordx4 v[76:79], v174, s[0:1] offset:32
	global_load_dwordx4 v[80:83], v174, s[0:1] offset:48
	global_load_dwordx4 v[84:87], v175, s[0:1]
	global_load_dwordx4 v[88:91], v175, s[0:1] offset:16
	global_load_dwordx4 v[92:95], v175, s[0:1] offset:32
	global_load_dwordx4 v[96:99], v175, s[0:1] offset:48
	s_waitcnt vmcnt(25)
	v_pk_fma_f32 v[36:37], v[100:101], v[2:3], v[36:37] op_sel_hi:[1,0,1]
	v_pk_fma_f32 v[38:39], v[102:103], v[2:3], v[38:39] op_sel_hi:[1,0,1]
	s_waitcnt vmcnt(24)
	v_pk_fma_f32 v[40:41], v[104:105], v[2:3], v[40:41] op_sel_hi:[1,0,1]
	v_pk_fma_f32 v[42:43], v[106:107], v[2:3], v[42:43] op_sel_hi:[1,0,1]
	s_waitcnt vmcnt(23)
	v_pk_fma_f32 v[44:45], v[108:109], v[2:3], v[44:45] op_sel_hi:[1,0,1]
	v_pk_fma_f32 v[46:47], v[110:111], v[2:3], v[46:47] op_sel_hi:[1,0,1]
	s_waitcnt vmcnt(22)
	v_pk_fma_f32 v[48:49], v[112:113], v[2:3], v[48:49] op_sel_hi:[1,0,1]
	v_pk_fma_f32 v[50:51], v[114:115], v[2:3], v[50:51] op_sel_hi:[1,0,1]
	s_waitcnt vmcnt(21)
	v_pk_fma_f32 v[52:53], v[116:117], v[2:3], v[52:53] op_sel_hi:[1,0,1]
	v_pk_fma_f32 v[54:55], v[118:119], v[2:3], v[54:55] op_sel_hi:[1,0,1]
	s_waitcnt vmcnt(20)
	v_pk_fma_f32 v[56:57], v[120:121], v[2:3], v[56:57] op_sel_hi:[1,0,1]
	v_pk_fma_f32 v[58:59], v[122:123], v[2:3], v[58:59] op_sel_hi:[1,0,1]
	s_waitcnt vmcnt(19)
	v_pk_fma_f32 v[60:61], v[124:125], v[2:3], v[60:61] op_sel_hi:[1,0,1]
	v_pk_fma_f32 v[62:63], v[126:127], v[2:3], v[62:63] op_sel_hi:[1,0,1]
	s_waitcnt vmcnt(18)
	v_pk_fma_f32 v[64:65], v[128:129], v[2:3], v[64:65] op_sel_hi:[1,0,1]
	v_pk_fma_f32 v[66:67], v[130:131], v[2:3], v[66:67] op_sel_hi:[1,0,1]
	s_add_i32 s55, s54, -2
	s_max_i32 s55, s55, 0
	s_add_i32 s0, s3, s55
	s_mul_hi_u32 s1, s0, 0x4200
	s_mulk_i32 s0, 0x4200
	s_add_u32 s0, s60, s0
	s_addc_u32 s1, s61, s1
	global_load_dword v138, v176, s[0:1]
	global_load_dword v139, v177, s[0:1]
	global_load_dwordx4 v[100:103], v172, s[0:1]
	global_load_dwordx4 v[104:107], v172, s[0:1] offset:16
	global_load_dwordx4 v[108:111], v172, s[0:1] offset:32
	global_load_dwordx4 v[112:115], v172, s[0:1] offset:48
	global_load_dwordx4 v[116:119], v173, s[0:1]
	global_load_dwordx4 v[120:123], v173, s[0:1] offset:16
	global_load_dwordx4 v[124:127], v173, s[0:1] offset:32
	global_load_dwordx4 v[128:131], v173, s[0:1] offset:48
	v_fmac_f32_e32 v226, v2, v134
	v_mul_f32_e32 v178, 0x3fb8aa3b, v135
	v_exp_f32_e32 v178, v178
	s_nop 1
	v_mul_f32_e32 v2, v2, v178
	s_add_i32 s54, s54, -1
	s_cmp_lt_i32 s54, 0
	s_cbranch_scc1 .Lpf_done
; template <bool OUT>
; __device__ __forceinline__ void mlstm_item(const bf16* u, bf16* y, float* scratch, const float* convw, const float* ib, const float* fbias, const float* normw, LAS unsigned char* wl, int bh, int c, int lane) {
;     ...
;             const float* s0 = scratch + (size_t)(bh * 16 + cp) * ML_ITEM_F;
;             f32x16 v0[4];
; #pragma unroll
;             for (int blk = 0; blk < 4; ++blk) v0[blk] = *(const f32x16*)(s0 + blk * 1024 + lane * 16);
;             const float n0 = s0[4096 + lane], g0 = s0[4160];
; #pragma unroll
;             for (int blk = 0; blk < 4; ++blk) X[blk >> 1][blk & 1] += v0[blk] * dec;
;             nk += dec * n0;
;             dec *= __expf(g0);
;         }
.Lpf_s1:
	s_waitcnt vmcnt(25)
	v_pk_fma_f32 v[4:5], v[228:229], v[2:3], v[4:5] op_sel_hi:[1,0,1]
	v_pk_fma_f32 v[6:7], v[230:231], v[2:3], v[6:7] op_sel_hi:[1,0,1]
	s_waitcnt vmcnt(24)
	v_pk_fma_f32 v[8:9], v[232:233], v[2:3], v[8:9] op_sel_hi:[1,0,1]
	v_pk_fma_f32 v[10:11], v[234:235], v[2:3], v[10:11] op_sel_hi:[1,0,1]
	s_waitcnt vmcnt(23)
	v_pk_fma_f32 v[12:13], v[236:237], v[2:3], v[12:13] op_sel_hi:[1,0,1]
	v_pk_fma_f32 v[14:15], v[238:239], v[2:3], v[14:15] op_sel_hi:[1,0,1]
	s_waitcnt vmcnt(22)
	v_pk_fma_f32 v[16:17], v[240:241], v[2:3], v[16:17] op_sel_hi:[1,0,1]
	v_pk_fma_f32 v[18:19], v[242:243], v[2:3], v[18:19] op_sel_hi:[1,0,1]
	s_waitcnt vmcnt(21)
	v_pk_fma_f32 v[20:21], v[244:245], v[2:3], v[20:21] op_sel_hi:[1,0,1]
	v_pk_fma_f32 v[22:23], v[246:247], v[2:3], v[22:23] op_sel_hi:[1,0,1]
	s_waitcnt vmcnt(20)
	v_pk_fma_f32 v[24:25], v[248:249], v[2:3], v[24:25] op_sel_hi:[1,0,1]
	v_pk_fma_f32 v[26:27], v[250:251], v[2:3], v[26:27] op_sel_hi:[1,0,1]
	s_waitcnt vmcnt(19)
	v_pk_fma_f32 v[28:29], v[164:165], v[2:3], v[28:29] op_sel_hi:[1,0,1]
	v_pk_fma_f32 v[30:31], v[166:167], v[2:3], v[30:31] op_sel_hi:[1,0,1]
	s_waitcnt vmcnt(18)
	v_pk_fma_f32 v[32:33], v[168:169], v[2:3], v[32:33] op_sel_hi:[1,0,1]
	v_pk_fma_f32 v[34:35], v[170:171], v[2:3], v[34:35] op_sel_hi:[1,0,1]
	s_add_i32 s55, s54, -1
	s_max_i32 s55, s55, 0
	s_add_i32 s0, s3, s55
	s_mul_hi_u32 s1, s0, 0x4200
	s_mulk_i32 s0, 0x4200
	s_add_u32 s0, s60, s0
	s_addc_u32 s1, s61, s1
	global_load_dwordx4 v[228:231], v174, s[0:1]
	global_load_dwordx4 v[232:235], v174, s[0:1] offset:16
	global_load_dwordx4 v[236:239], v174, s[0:1] offset:32
	global_load_dwordx4 v[240:243], v174, s[0:1] offset:48
	global_load_dwordx4 v[244:247], v175, s[0:1]
	global_load_dwordx4 v[248:251], v175, s[0:1] offset:16
	global_load_dwordx4 v[164:167], v175, s[0:1] offset:32
	global_load_dwordx4 v[168:171], v175, s[0:1] offset:48
	s_waitcnt vmcnt(25)
	v_pk_fma_f32 v[36:37], v[68:69], v[2:3], v[36:37] op_sel_hi:[1,0,1]
	v_pk_fma_f32 v[38:39], v[70:71], v[2:3], v[38:39] op_sel_hi:[1,0,1]
	s_waitcnt vmcnt(24)
	v_pk_fma_f32 v[40:41], v[72:73], v[2:3], v[40:41] op_sel_hi:[1,0,1]
	v_pk_fma_f32 v[42:43], v[74:75], v[2:3], v[42:43] op_sel_hi:[1,0,1]
	s_waitcnt vmcnt(23)
	v_pk_fma_f32 v[44:45], v[76:77], v[2:3], v[44:45] op_sel_hi:[1,0,1]
	v_pk_fma_f32 v[46:47], v[78:79], v[2:3], v[46:47] op_sel_hi:[1,0,1]
	s_waitcnt vmcnt(22)
	v_pk_fma_f32 v[48:49], v[80:81], v[2:3], v[48:49] op_sel_hi:[1,0,1]
	v_pk_fma_f32 v[50:51], v[82:83], v[2:3], v[50:51] op_sel_hi:[1,0,1]
	s_waitcnt vmcnt(21)
	v_pk_fma_f32 v[52:53], v[84:85], v[2:3], v[52:53] op_sel_hi:[1,0,1]
	v_pk_fma_f32 v[54:55], v[86:87], v[2:3], v[54:55] op_sel_hi:[1,0,1]
	s_waitcnt vmcnt(20)
	v_pk_fma_f32 v[56:57], v[88:89], v[2:3], v[56:57] op_sel_hi:[1,0,1]
	v_pk_fma_f32 v[58:59], v[90:91], v[2:3], v[58:59] op_sel_hi:[1,0,1]
	s_waitcnt vmcnt(19)
	v_pk_fma_f32 v[60:61], v[92:93], v[2:3], v[60:61] op_sel_hi:[1,0,1]
	v_pk_fma_f32 v[62:63], v[94:95], v[2:3], v[62:63] op_sel_hi:[1,0,1]
	s_waitcnt vmcnt(18)
	v_pk_fma_f32 v[64:65], v[96:97], v[2:3], v[64:65] op_sel_hi:[1,0,1]
	v_pk_fma_f32 v[66:67], v[98:99], v[2:3], v[66:67] op_sel_hi:[1,0,1]
	s_add_i32 s55, s54, -2
	s_max_i32 s55, s55, 0
	s_add_i32 s0, s3, s55
	s_mul_hi_u32 s1, s0, 0x4200
	s_mulk_i32 s0, 0x4200
	s_add_u32 s0, s60, s0
	s_addc_u32 s1, s61, s1
	global_load_dword v134, v176, s[0:1]
	global_load_dword v135, v177, s[0:1]
	global_load_dwordx4 v[68:71], v172, s[0:1]
	global_load_dwordx4 v[72:75], v172, s[0:1] offset:16
	global_load_dwordx4 v[76:79], v172, s[0:1] offset:32
	global_load_dwordx4 v[80:83], v172, s[0:1] offset:48
	global_load_dwordx4 v[84:87], v173, s[0:1]
	global_load_dwordx4 v[88:91], v173, s[0:1] offset:16
	global_load_dwordx4 v[92:95], v173, s[0:1] offset:32
	global_load_dwordx4 v[96:99], v173, s[0:1] offset:48
	v_fmac_f32_e32 v226, v2, v136
	v_mul_f32_e32 v178, 0x3fb8aa3b, v137
	v_exp_f32_e32 v178, v178
	s_nop 1
	v_mul_f32_e32 v2, v2, v178
	s_add_i32 s54, s54, -1
	s_cmp_lt_i32 s54, 0
	s_cbranch_scc1 .Lpf_done
; template <bool OUT>
; __device__ __forceinline__ void mlstm_item(const bf16* u, bf16* y, float* scratch, const float* convw, const float* ib, const float* fbias, const float* normw, LAS unsigned char* wl, int bh, int c, int lane) {
;     ...
;             const float* s0 = scratch + (size_t)(bh * 16 + cp) * ML_ITEM_F;
;             f32x16 v0[4];
; #pragma unroll
;             for (int blk = 0; blk < 4; ++blk) v0[blk] = *(const f32x16*)(s0 + blk * 1024 + lane * 16);
;             const float n0 = s0[4096 + lane], g0 = s0[4160];
; #pragma unroll
;             for (int blk = 0; blk < 4; ++blk) X[blk >> 1][blk & 1] += v0[blk] * dec;
;             nk += dec * n0;
;             dec *= __expf(g0);
;         }
.Lpf_s2:
	s_waitcnt vmcnt(25)
	v_pk_fma_f32 v[4:5], v[100:101], v[2:3], v[4:5] op_sel_hi:[1,0,1]
	v_pk_fma_f32 v[6:7], v[102:103], v[2:3], v[6:7] op_sel_hi:[1,0,1]
	s_waitcnt vmcnt(24)
	v_pk_fma_f32 v[8:9], v[104:105], v[2:3], v[8:9] op_sel_hi:[1,0,1]
	v_pk_fma_f32 v[10:11], v[106:107], v[2:3], v[10:11] op_sel_hi:[1,0,1]
	s_waitcnt vmcnt(23)
	v_pk_fma_f32 v[12:13], v[108:109], v[2:3], v[12:13] op_sel_hi:[1,0,1]
	v_pk_fma_f32 v[14:15], v[110:111], v[2:3], v[14:15] op_sel_hi:[1,0,1]
	s_waitcnt vmcnt(22)
	v_pk_fma_f32 v[16:17], v[112:113], v[2:3], v[16:17] op_sel_hi:[1,0,1]
	v_pk_fma_f32 v[18:19], v[114:115], v[2:3], v[18:19] op_sel_hi:[1,0,1]
	s_waitcnt vmcnt(21)
	v_pk_fma_f32 v[20:21], v[116:117], v[2:3], v[20:21] op_sel_hi:[1,0,1]
	v_pk_fma_f32 v[22:23], v[118:119], v[2:3], v[22:23] op_sel_hi:[1,0,1]
	s_waitcnt vmcnt(20)
	v_pk_fma_f32 v[24:25], v[120:121], v[2:3], v[24:25] op_sel_hi:[1,0,1]
	v_pk_fma_f32 v[26:27], v[122:123], v[2:3], v[26:27] op_sel_hi:[1,0,1]
	s_waitcnt vmcnt(19)
	v_pk_fma_f32 v[28:29], v[124:125], v[2:3], v[28:29] op_sel_hi:[1,0,1]
	v_pk_fma_f32 v[30:31], v[126:127], v[2:3], v[30:31] op_sel_hi:[1,0,1]
	s_waitcnt vmcnt(18)
	v_pk_fma_f32 v[32:33], v[128:129], v[2:3], v[32:33] op_sel_hi:[1,0,1]
	v_pk_fma_f32 v[34:35], v[130:131], v[2:3], v[34:35] op_sel_hi:[1,0,1]
	s_add_i32 s55, s54, -1
	s_max_i32 s55, s55, 0
	s_add_i32 s0, s3, s55
	s_mul_hi_u32 s1, s0, 0x4200
	s_mulk_i32 s0, 0x4200
	s_add_u32 s0, s60, s0
	s_addc_u32 s1, s61, s1
	global_load_dwordx4 v[100:103], v174, s[0:1]
	global_load_dwordx4 v[104:107], v174, s[0:1] offset:16
	global_load_dwordx4 v[108:111], v174, s[0:1] offset:32
	global_load_dwordx4 v[112:115], v174, s[0:1] offset:48
	global_load_dwordx4 v[116:119], v175, s[0:1]
	global_load_dwordx4 v[120:123], v175, s[0:1] offset:16
	global_load_dwordx4 v[124:127], v175, s[0:1] offset:32
	global_load_dwordx4 v[128:131], v175, s[0:1] offset:48
	s_waitcnt vmcnt(25)
	v_pk_fma_f32 v[36:37], v[228:229], v[2:3], v[36:37] op_sel_hi:[1,0,1]
	v_pk_fma_f32 v[38:39], v[230:231], v[2:3], v[38:39] op_sel_hi:[1,0,1]
	s_waitcnt vmcnt(24)
	v_pk_fma_f32 v[40:41], v[232:233], v[2:3], v[40:41] op_sel_hi:[1,0,1]
	v_pk_fma_f32 v[42:43], v[234:235], v[2:3], v[42:43] op_sel_hi:[1,0,1]
	s_waitcnt vmcnt(23)
	v_pk_fma_f32 v[44:45], v[236:237], v[2:3], v[44:45] op_sel_hi:[1,0,1]
	v_pk_fma_f32 v[46:47], v[238:239], v[2:3], v[46:47] op_sel_hi:[1,0,1]
	s_waitcnt vmcnt(22)
	v_pk_fma_f32 v[48:49], v[240:241], v[2:3], v[48:49] op_sel_hi:[1,0,1]
	v_pk_fma_f32 v[50:51], v[242:243], v[2:3], v[50:51] op_sel_hi:[1,0,1]
	s_waitcnt vmcnt(21)
	v_pk_fma_f32 v[52:53], v[244:245], v[2:3], v[52:53] op_sel_hi:[1,0,1]
	v_pk_fma_f32 v[54:55], v[246:247], v[2:3], v[54:55] op_sel_hi:[1,0,1]
	s_waitcnt vmcnt(20)
	v_pk_fma_f32 v[56:57], v[248:249], v[2:3], v[56:57] op_sel_hi:[1,0,1]
	v_pk_fma_f32 v[58:59], v[250:251], v[2:3], v[58:59] op_sel_hi:[1,0,1]
	s_waitcnt vmcnt(19)
	v_pk_fma_f32 v[60:61], v[164:165], v[2:3], v[60:61] op_sel_hi:[1,0,1]
	v_pk_fma_f32 v[62:63], v[166:167], v[2:3], v[62:63] op_sel_hi:[1,0,1]
	s_waitcnt vmcnt(18)
	v_pk_fma_f32 v[64:65], v[168:169], v[2:3], v[64:65] op_sel_hi:[1,0,1]
	v_pk_fma_f32 v[66:67], v[170:171], v[2:3], v[66:67] op_sel_hi:[1,0,1]
	s_add_i32 s55, s54, -2
	s_max_i32 s55, s55, 0
	s_add_i32 s0, s3, s55
	s_mul_hi_u32 s1, s0, 0x4200
	s_mulk_i32 s0, 0x4200
	s_add_u32 s0, s60, s0
	s_addc_u32 s1, s61, s1
	global_load_dword v136, v176, s[0:1]
	global_load_dword v137, v177, s[0:1]
	global_load_dwordx4 v[228:231], v172, s[0:1]
	global_load_dwordx4 v[232:235], v172, s[0:1] offset:16
	global_load_dwordx4 v[236:239], v172, s[0:1] offset:32
	global_load_dwordx4 v[240:243], v172, s[0:1] offset:48
	global_load_dwordx4 v[244:247], v173, s[0:1]
	global_load_dwordx4 v[248:251], v173, s[0:1] offset:16
	global_load_dwordx4 v[164:167], v173, s[0:1] offset:32
	global_load_dwordx4 v[168:171], v173, s[0:1] offset:48
	v_fmac_f32_e32 v226, v2, v138
	v_mul_f32_e32 v178, 0x3fb8aa3b, v139
	v_exp_f32_e32 v178, v178
	s_nop 1
	v_mul_f32_e32 v2, v2, v178
	s_add_i32 s54, s54, -1
	s_cmp_lt_i32 s54, 0
	s_cbranch_scc1 .Lpf_done
	s_branch .Lpf_s0
.Lpf_done:
	s_waitcnt vmcnt(0)
	s_branch .LBB0_786
